# v56 plus nt hint on the P2 hgrn_a item loads (LOGF and V rows)
# baseline (speedup 1.0000x reference)
.LBB0_806:
	s_lshl_b32 s12, s94, 4
	v_and_b32_e32 v11, 15, v0
	s_waitcnt lgkmcnt(0)
	v_or_b32_e32 v2, s12, v11
	v_lshrrev_b32_e32 v4, 1, v187
	v_and_b32_e32 v1, 24, v4
	v_lshlrev_b32_e32 v36, 2, v2
	v_mov_b32_e32 v37, 0
	s_lshl_b32 s6, s6, 7
	v_lshl_add_u64 v[2:3], s[16:17], 0, v[36:37]
	s_mov_b64 s[10:11], 0x57100000
	s_and_b32 s9, s6, 0x780
	v_add_u32_e32 v6, s3, v1
	v_or_b32_e32 v36, 1, v1
	s_waitcnt vmcnt(0)
	v_or_b32_e32 v56, 2, v1
	v_or_b32_e32 v57, 3, v1
	v_or_b32_e32 v58, 4, v1
	v_or_b32_e32 v59, 5, v1
	v_or_b32_e32 v60, 6, v1
	v_or_b32_e32 v61, 7, v4
	s_mov_b32 s7, 0
	v_lshl_add_u64 v[34:35], v[2:3], 0, s[10:11]
	s_lshl_b32 s6, s9, 2
	v_ashrrev_i32_e32 v7, 31, v6
	v_add_u32_e32 v8, s3, v36
	v_add_u32_e32 v12, s3, v56
	v_add_u32_e32 v14, s3, v57
	v_add_u32_e32 v16, s3, v58
	v_add_u32_e32 v18, s3, v59
	v_add_u32_e32 v20, s3, v60
	v_add_u32_e32 v22, s3, v61
	v_lshl_add_u64 v[2:3], v[34:35], 0, s[6:7]
	v_lshlrev_b64 v[6:7], 13, v[6:7]
	v_ashrrev_i32_e32 v9, 31, v8
	v_ashrrev_i32_e32 v13, 31, v12
	v_ashrrev_i32_e32 v15, 31, v14
	v_ashrrev_i32_e32 v17, 31, v16
	v_ashrrev_i32_e32 v19, 31, v18
	v_ashrrev_i32_e32 v21, 31, v20
	v_ashrrev_i32_e32 v23, 31, v22
	v_lshl_add_u64 v[6:7], v[2:3], 0, v[6:7]
	v_lshlrev_b64 v[8:9], 13, v[8:9]
	v_lshlrev_b64 v[12:13], 13, v[12:13]
	v_lshlrev_b64 v[14:15], 13, v[14:15]
	v_lshlrev_b64 v[16:17], 13, v[16:17]
	v_lshlrev_b64 v[18:19], 13, v[18:19]
	v_lshlrev_b64 v[20:21], 13, v[20:21]
	v_lshlrev_b64 v[22:23], 13, v[22:23]
	v_lshl_add_u64 v[8:9], v[2:3], 0, v[8:9]
	v_lshl_add_u64 v[12:13], v[2:3], 0, v[12:13]
	v_lshl_add_u64 v[14:15], v[2:3], 0, v[14:15]
	v_lshl_add_u64 v[16:17], v[2:3], 0, v[16:17]
	v_lshl_add_u64 v[18:19], v[2:3], 0, v[18:19]
	v_lshl_add_u64 v[20:21], v[2:3], 0, v[20:21]
	v_lshl_add_u64 v[22:23], v[2:3], 0, v[22:23]
	flat_load_dword v62, v[6:7] nt
	flat_load_dword v63, v[8:9] nt
	flat_load_dword v64, v[12:13] nt
	flat_load_dword v65, v[14:15] nt
	flat_load_dword v66, v[16:17] nt
	flat_load_dword v67, v[18:19] nt
	flat_load_dword v68, v[20:21] nt
	flat_load_dword v69, v[22:23] nt
	v_or_b32_e32 v70, 32, v1
	v_cmp_gt_u32_e32 vcc, s8, v70
	v_mov_b32_e32 v71, 0
	s_and_saveexec_b64 s[6:7], vcc
	s_cbranch_execz .LBB0_808
	v_add_u32_e32 v6, s3, v70
	v_ashrrev_i32_e32 v7, 31, v6
	v_lshlrev_b64 v[6:7], 13, v[6:7]
	v_lshl_add_u64 v[6:7], v[2:3], 0, v[6:7]
	flat_load_dword v71, v[6:7] nt
.LBB0_808:
	s_or_b64 exec, exec, s[6:7]
	v_or_b32_e32 v72, 33, v1
	v_cmp_gt_u32_e32 vcc, s8, v72
	s_and_saveexec_b64 s[6:7], vcc
	s_cbranch_execz .LBB0_810
	v_add_u32_e32 v6, s3, v72
	v_ashrrev_i32_e32 v7, 31, v6
	v_lshlrev_b64 v[6:7], 13, v[6:7]
	v_lshl_add_u64 v[6:7], v[2:3], 0, v[6:7]
	flat_load_dword v37, v[6:7] nt
.LBB0_810:
	s_or_b64 exec, exec, s[6:7]
	v_or_b32_e32 v73, 34, v1
	v_cmp_gt_u32_e32 vcc, s8, v73
	v_mov_b32_e32 v76, 0
	v_mov_b32_e32 v75, 0
	s_and_saveexec_b64 s[6:7], vcc
	s_cbranch_execz .LBB0_812
	v_add_u32_e32 v6, s3, v73
	v_ashrrev_i32_e32 v7, 31, v6
	v_lshlrev_b64 v[6:7], 13, v[6:7]
	v_lshl_add_u64 v[6:7], v[2:3], 0, v[6:7]
	flat_load_dword v75, v[6:7] nt
.LBB0_812:
	s_or_b64 exec, exec, s[6:7]
	v_or_b32_e32 v74, 35, v1
	v_cmp_gt_u32_e32 vcc, s8, v74
	s_and_saveexec_b64 s[6:7], vcc
	s_cbranch_execz .LBB0_814
	v_add_u32_e32 v6, s3, v74
	v_ashrrev_i32_e32 v7, 31, v6
	v_lshlrev_b64 v[6:7], 13, v[6:7]
	v_lshl_add_u64 v[6:7], v[2:3], 0, v[6:7]
	flat_load_dword v76, v[6:7] nt
.LBB0_814:
	s_or_b64 exec, exec, s[6:7]
	v_or_b32_e32 v77, 36, v1
	v_cmp_gt_u32_e32 vcc, s8, v77
	v_mov_b32_e32 v80, 0
	v_mov_b32_e32 v79, 0
	s_and_saveexec_b64 s[6:7], vcc
	s_cbranch_execz .LBB0_816
	v_add_u32_e32 v6, s3, v77
	v_ashrrev_i32_e32 v7, 31, v6
	v_lshlrev_b64 v[6:7], 13, v[6:7]
	v_lshl_add_u64 v[6:7], v[2:3], 0, v[6:7]
	flat_load_dword v79, v[6:7] nt
.LBB0_816:
	s_or_b64 exec, exec, s[6:7]
	v_or_b32_e32 v78, 37, v1
	v_cmp_gt_u32_e32 vcc, s8, v78
	s_and_saveexec_b64 s[6:7], vcc
	s_cbranch_execz .LBB0_818
	v_add_u32_e32 v6, s3, v78
	v_ashrrev_i32_e32 v7, 31, v6
	v_lshlrev_b64 v[6:7], 13, v[6:7]
	v_lshl_add_u64 v[6:7], v[2:3], 0, v[6:7]
	flat_load_dword v80, v[6:7] nt
.LBB0_818:
	s_or_b64 exec, exec, s[6:7]
	v_or_b32_e32 v81, 38, v1
	v_cmp_gt_u32_e32 vcc, s8, v81
	v_mov_b32_e32 v84, 0
	v_mov_b32_e32 v83, 0
	s_and_saveexec_b64 s[6:7], vcc
	s_cbranch_execz .LBB0_820
	v_add_u32_e32 v6, s3, v81
	v_ashrrev_i32_e32 v7, 31, v6
	v_lshlrev_b64 v[6:7], 13, v[6:7]
	v_lshl_add_u64 v[6:7], v[2:3], 0, v[6:7]
	flat_load_dword v83, v[6:7] nt
.LBB0_820:
	s_or_b64 exec, exec, s[6:7]
	v_or_b32_e32 v82, 39, v4
	v_cmp_gt_u32_e32 vcc, s8, v82
	s_and_saveexec_b64 s[6:7], vcc
	s_cbranch_execz .LBB0_822
	v_add_u32_e32 v4, s3, v82
	v_ashrrev_i32_e32 v5, 31, v4
	v_lshlrev_b64 v[4:5], 13, v[4:5]
	v_lshl_add_u64 v[2:3], v[2:3], 0, v[4:5]
	flat_load_dword v84, v[2:3] nt
.LBB0_822:
	s_or_b64 exec, exec, s[6:7]
	v_lshlrev_b32_e32 v2, 3, v0
	v_and_b32_e32 v10, 0x78, v2
	v_mov_b32_e32 v2, 0
	v_mov_b32_e32 v4, v2
	v_mov_b32_e32 v5, v2
	s_add_u32 s18, s16, 0x32800000
	v_lshrrev_b32_e32 v85, 4, v0
	v_mov_b32_e32 v3, v2
	v_mov_b64_e32 v[8:9], v[4:5]
	s_addc_u32 s19, s17, 0
	v_cmp_gt_u32_e32 vcc, s8, v85
	s_mov_b32 s21, 0
	v_lshlrev_b32_e32 v38, 1, v10
	v_mov_b64_e32 v[6:7], v[2:3]
	s_and_saveexec_b64 s[6:7], vcc
	s_cbranch_execz .LBB0_824
	v_add_u32_e32 v8, s3, v85
	s_mov_b32 s10, 0x9000
	v_mov_b64_e32 v[6:7], s[18:19]
	v_mad_i64_i32 v[6:7], s[10:11], v8, s10, v[6:7]
	s_lshl_b32 s20, s9, 1
	v_lshl_add_u64 v[6:7], v[6:7], 0, s[20:21]
	v_mov_b32_e32 v39, v2
	v_lshl_add_u64 v[6:7], v[6:7], 0, v[38:39]
	v_add_co_u32_e32 v6, vcc, 0x3000, v6
	s_nop 1
	v_addc_co_u32_e32 v7, vcc, 0, v7, vcc
	flat_load_dwordx4 v[6:9], v[6:7] nt
.LBB0_824:
	s_or_b64 exec, exec, s[6:7]
	v_or_b32_e32 v12, 0x200, v0
	v_lshrrev_b32_e32 v86, 4, v12
	v_cmp_gt_u32_e32 vcc, s8, v86
	s_and_saveexec_b64 s[6:7], vcc
	s_cbranch_execz .LBB0_826
	v_add_u32_e32 v4, s3, v86
	s_mov_b32 s3, 0x9000
	v_mov_b64_e32 v[2:3], s[18:19]
	v_mad_i64_i32 v[2:3], s[10:11], v4, s3, v[2:3]
	s_lshl_b32 s20, s9, 1
	v_lshl_add_u64 v[2:3], v[2:3], 0, s[20:21]
	v_mov_b32_e32 v39, 0
	v_lshl_add_u64 v[2:3], v[2:3], 0, v[38:39]
	v_add_co_u32_e32 v2, vcc, 0x3000, v2
	s_nop 1
	v_addc_co_u32_e32 v3, vcc, 0, v3, vcc
	flat_load_dwordx4 v[2:5], v[2:3] nt

.LBB0_832:
	s_lshl_b32 s12, s12, 7
	s_and_b32 s37, s12, 0x780
	v_add_u32_e32 v14, s35, v1
	s_lshl_b32 s20, s37, 2
	v_ashrrev_i32_e32 v15, 31, v14
	v_add_u32_e32 v16, s35, v36
	v_add_u32_e32 v18, s35, v56
	v_add_u32_e32 v20, s35, v57
	v_add_u32_e32 v22, s35, v58
	v_add_u32_e32 v24, s35, v59
	v_add_u32_e32 v26, s35, v60
	v_add_u32_e32 v28, s35, v61
	v_lshl_add_u64 v[12:13], v[34:35], 0, s[20:21]
	v_lshlrev_b64 v[14:15], 13, v[14:15]
	v_ashrrev_i32_e32 v17, 31, v16
	v_ashrrev_i32_e32 v19, 31, v18
	v_ashrrev_i32_e32 v21, 31, v20
	v_ashrrev_i32_e32 v23, 31, v22
	v_ashrrev_i32_e32 v25, 31, v24
	v_ashrrev_i32_e32 v27, 31, v26
	v_ashrrev_i32_e32 v29, 31, v28
	v_lshl_add_u64 v[14:15], v[12:13], 0, v[14:15]
	v_lshlrev_b64 v[16:17], 13, v[16:17]
	v_lshlrev_b64 v[18:19], 13, v[18:19]
	v_lshlrev_b64 v[20:21], 13, v[20:21]
	v_lshlrev_b64 v[22:23], 13, v[22:23]
	v_lshlrev_b64 v[24:25], 13, v[24:25]
	v_lshlrev_b64 v[26:27], 13, v[26:27]
	v_lshlrev_b64 v[28:29], 13, v[28:29]
	v_lshl_add_u64 v[16:17], v[12:13], 0, v[16:17]
	v_lshl_add_u64 v[18:19], v[12:13], 0, v[18:19]
	v_lshl_add_u64 v[20:21], v[12:13], 0, v[20:21]
	v_lshl_add_u64 v[22:23], v[12:13], 0, v[22:23]
	v_lshl_add_u64 v[24:25], v[12:13], 0, v[24:25]
	v_lshl_add_u64 v[26:27], v[12:13], 0, v[26:27]
	v_lshl_add_u64 v[28:29], v[12:13], 0, v[28:29]
	flat_load_dword v106, v[14:15] nt
	flat_load_dword v105, v[16:17] nt
	flat_load_dword v103, v[18:19] nt
	flat_load_dword v102, v[20:21] nt
	flat_load_dword v101, v[22:23] nt
	flat_load_dword v100, v[24:25] nt
	flat_load_dword v99, v[26:27] nt
	flat_load_dword v98, v[28:29] nt
	v_cmp_gt_u32_e32 vcc, s36, v70
	v_mov_b32_e32 v104, 0
	v_mov_b32_e32 v107, 0
	s_and_saveexec_b64 s[12:13], vcc
	s_cbranch_execz .LBB0_834
	v_add_u32_e32 v14, s35, v70
	v_ashrrev_i32_e32 v15, 31, v14
	v_lshlrev_b64 v[14:15], 13, v[14:15]
	v_lshl_add_u64 v[14:15], v[12:13], 0, v[14:15]
	flat_load_dword v107, v[14:15] nt
.LBB0_834:
	s_or_b64 exec, exec, s[12:13]
	v_cmp_gt_u32_e32 vcc, s36, v72
	s_and_saveexec_b64 s[12:13], vcc
	s_cbranch_execz .LBB0_836
	v_add_u32_e32 v14, s35, v72
	v_ashrrev_i32_e32 v15, 31, v14
	v_lshlrev_b64 v[14:15], 13, v[14:15]
	v_lshl_add_u64 v[14:15], v[12:13], 0, v[14:15]
	flat_load_dword v104, v[14:15] nt
.LBB0_836:
	s_or_b64 exec, exec, s[12:13]
	v_cmp_gt_u32_e32 vcc, s36, v73
	v_mov_b32_e32 v108, 0
	v_mov_b32_e32 v109, 0
	s_and_saveexec_b64 s[12:13], vcc
	s_cbranch_execz .LBB0_838
	v_add_u32_e32 v14, s35, v73
	v_ashrrev_i32_e32 v15, 31, v14
	v_lshlrev_b64 v[14:15], 13, v[14:15]
	v_lshl_add_u64 v[14:15], v[12:13], 0, v[14:15]
	flat_load_dword v109, v[14:15] nt
.LBB0_838:
	s_or_b64 exec, exec, s[12:13]
	v_cmp_gt_u32_e32 vcc, s36, v74
	s_and_saveexec_b64 s[12:13], vcc
	s_cbranch_execz .LBB0_840
	v_add_u32_e32 v14, s35, v74
	v_ashrrev_i32_e32 v15, 31, v14
	v_lshlrev_b64 v[14:15], 13, v[14:15]
	v_lshl_add_u64 v[14:15], v[12:13], 0, v[14:15]
	flat_load_dword v108, v[14:15] nt
.LBB0_840:
	s_or_b64 exec, exec, s[12:13]
	v_cmp_gt_u32_e32 vcc, s36, v77
	v_mov_b32_e32 v110, 0
	v_mov_b32_e32 v111, 0
	s_and_saveexec_b64 s[12:13], vcc
	s_cbranch_execz .LBB0_842
	v_add_u32_e32 v14, s35, v77
	v_ashrrev_i32_e32 v15, 31, v14
	v_lshlrev_b64 v[14:15], 13, v[14:15]
	v_lshl_add_u64 v[14:15], v[12:13], 0, v[14:15]
	flat_load_dword v111, v[14:15] nt
.LBB0_842:
	s_or_b64 exec, exec, s[12:13]
	v_cmp_gt_u32_e32 vcc, s36, v78
	s_and_saveexec_b64 s[12:13], vcc
	s_cbranch_execz .LBB0_844
	v_add_u32_e32 v14, s35, v78
	v_ashrrev_i32_e32 v15, 31, v14
	v_lshlrev_b64 v[14:15], 13, v[14:15]
	v_lshl_add_u64 v[14:15], v[12:13], 0, v[14:15]
	flat_load_dword v110, v[14:15] nt
.LBB0_844:
	s_or_b64 exec, exec, s[12:13]
	v_cmp_gt_u32_e32 vcc, s36, v81
	v_mov_b32_e32 v112, 0
	v_mov_b32_e32 v113, 0
	s_and_saveexec_b64 s[12:13], vcc
	s_cbranch_execz .LBB0_846
	v_add_u32_e32 v14, s35, v81
	v_ashrrev_i32_e32 v15, 31, v14
	v_lshlrev_b64 v[14:15], 13, v[14:15]
	v_lshl_add_u64 v[14:15], v[12:13], 0, v[14:15]
	flat_load_dword v113, v[14:15] nt
.LBB0_846:
	s_or_b64 exec, exec, s[12:13]
	v_cmp_gt_u32_e32 vcc, s36, v82
	s_and_saveexec_b64 s[12:13], vcc
	s_cbranch_execz .LBB0_848
	v_add_u32_e32 v14, s35, v82
	v_ashrrev_i32_e32 v15, 31, v14
	v_lshlrev_b64 v[14:15], 13, v[14:15]
	v_lshl_add_u64 v[12:13], v[12:13], 0, v[14:15]
	flat_load_dword v112, v[12:13] nt
.LBB0_848:
	s_or_b64 exec, exec, s[12:13]
	v_mov_b32_e32 v12, v10
	v_mov_b32_e32 v13, v10
	v_mov_b32_e32 v11, v10
	v_mov_b64_e32 v[16:17], v[12:13]
	v_cmp_gt_u32_e32 vcc, s36, v85
	v_mov_b64_e32 v[14:15], v[10:11]
	s_and_saveexec_b64 s[12:13], vcc
	s_cbranch_execz .LBB0_850
	v_add_u32_e32 v16, s35, v85
	v_mov_b64_e32 v[14:15], s[18:19]
	v_mad_i64_i32 v[14:15], s[56:57], v16, s46, v[14:15]
	s_lshl_b32 s20, s37, 1
	v_lshl_add_u64 v[14:15], v[14:15], 0, s[20:21]
	v_mov_b32_e32 v39, v10
	v_lshl_add_u64 v[14:15], v[14:15], 0, v[38:39]
	v_add_co_u32_e32 v14, vcc, 0x3000, v14
	s_nop 1
	v_addc_co_u32_e32 v15, vcc, 0, v15, vcc
	flat_load_dwordx4 v[14:17], v[14:15] nt
.LBB0_850:
	s_or_b64 exec, exec, s[12:13]
	v_mov_b64_e32 v[20:21], v[12:13]
	v_cmp_gt_u32_e32 vcc, s36, v86
	v_mov_b64_e32 v[18:19], v[10:11]
	s_and_saveexec_b64 s[12:13], vcc
	s_cbranch_execz .LBB0_852
	v_add_u32_e32 v11, s35, v86
	v_mov_b64_e32 v[12:13], s[18:19]
	v_mad_i64_i32 v[12:13], s[56:57], v11, s46, v[12:13]
	s_lshl_b32 s20, s37, 1
	v_lshl_add_u64 v[12:13], v[12:13], 0, s[20:21]
	v_mov_b32_e32 v39, v10
	v_lshl_add_u64 v[12:13], v[12:13], 0, v[38:39]
	v_add_co_u32_e32 v12, vcc, 0x3000, v12
	s_nop 1
	v_addc_co_u32_e32 v13, vcc, 0, v13, vcc
	flat_load_dwordx4 v[18:21], v[12:13] nt
